# k16 + mLSTM scan: next chunk's prefetch loads issued before the staging publish barrier instead of after it
# speedup vs baseline: 1.0122x; 1.0074x over previous
.LBB0_1916:
	s_or_b64 exec, exec, s[0:1]
	s_add_i32 s83, s82, 1
	s_cmpk_eq_i32 s82, 0x43
	s_cbranch_scc1 .LBB0_1925
	s_cmp_lt_u32 s82, 3
	s_cselect_b32 s0, 3, 0x47
	s_add_i32 s28, s0, s81
	s_and_b64 s[0:1], s[44:45], exec
	s_cselect_b32 s0, s83, s28
	s_add_i32 s40, s0, s78
	s_lshl_b64 s[28:29], s[40:41], 13
	s_lshl_b64 s[46:47], s[40:41], 15
	s_add_u32 s84, s25, s46
	s_addc_u32 s85, s11, s47
	s_add_u32 s46, s50, s46
	v_lshl_add_u64 v[4:5], v[114:115], 0, s[28:29]
	s_addc_u32 s47, s33, s47
	global_load_dwordx4 v[6:9], v[4:5], off
	v_lshl_add_u64 v[4:5], s[84:85], 0, v[100:101]
	global_load_dwordx4 v[10:13], v[4:5], off
	v_lshl_add_u64 v[4:5], s[46:47], 0, v[98:99]
	global_load_dwordx4 v[14:17], v[4:5], off
	v_lshl_add_u64 v[4:5], s[84:85], 0, v[102:103]
	global_load_dwordx4 v[18:21], v[4:5], off
	v_lshl_add_u64 v[4:5], s[46:47], 0, v[104:105]
	global_load_dwordx4 v[22:25], v[4:5], off
	v_lshl_add_u64 v[4:5], s[84:85], 0, v[106:107]
	global_load_dwordx4 v[30:33], v[4:5], off
	v_lshl_add_u64 v[4:5], s[46:47], 0, v[108:109]
	global_load_dwordx4 v[34:37], v[4:5], off
	v_lshl_add_u64 v[4:5], s[84:85], 0, v[110:111]
	global_load_dwordx4 v[38:41], v[4:5], off
	v_lshl_add_u64 v[4:5], s[46:47], 0, v[112:113]
	global_load_dwordx4 v[42:45], v[4:5], off
	s_and_saveexec_b64 s[46:47], vcc
	s_cbranch_execz .LBB0_1928
	s_ashr_i32 s1, s0, 31
	s_lshl_b64 s[0:1], s[0:1], 15
	v_lshl_add_u64 v[4:5], v[116:117], 0, s[0:1]
	global_load_dwordx4 v[26:29], v[4:5], off
	s_or_b64 exec, exec, s[46:47]
	s_and_saveexec_b64 s[0:1], vcc
	s_cbranch_execnz .LBB0_1929

.LBB0_1921:
	s_or_b64 exec, exec, s[0:1]
	s_waitcnt lgkmcnt(0)
	s_barrier
	s_and_saveexec_b64 s[0:1], s[8:9]
	s_xor_b64 s[0:1], exec, s[0:1]
	s_cbranch_execnz .LBB0_1926

.LBB0_1925:
	s_waitcnt lgkmcnt(0)
	s_barrier
	s_and_saveexec_b64 s[0:1], s[8:9]
	s_xor_b64 s[0:1], exec, s[0:1]
	s_cbranch_execz .LBB0_1922
